# sample-MLA value MFMAs: the wave that also computes scores this step gets priority 3 (partner stays 1); plus double-buffered score fragments, G2 loop, lean past-K epilogue
# baseline (speedup 1.0000x reference)
.LBB0_1144:
	s_mul_hi_u32 s19, s17, 0xcccccccd
	s_lshr_b32 s19, s19, 2
	s_mul_i32 s19, s19, 0x14000
	v_subrev_u32_e32 v142, s19, v240
	s_mul_hi_u32 s19, s25, 0xcccccccd
	s_lshr_b32 s19, s19, 2
	s_mul_i32 s19, s19, 0x14000
	v_subrev_u32_e32 v143, s19, v241
	s_add_i32 s19, s9, 0
	s_waitcnt lgkmcnt(0)
	v_add_u32_e32 v200, s19, v143
	v_add_u32_e32 v1, s19, v142
	ds_read_b64_tr_b16 v[142:143], v200 offset:0
	ds_read_b64_tr_b16 v[144:145], v200 offset:8192
	ds_read_b64_tr_b16 v[146:147], v200 offset:512
	ds_read_b64_tr_b16 v[148:149], v200 offset:8704
	ds_read_b64_tr_b16 v[248:249], v200 offset:1024
	ds_read_b64_tr_b16 v[250:251], v200 offset:9216
	s_cmp_lg_u64 s[66:67], 0
	s_cbranch_scc1 .Lpv_busy
	s_setprio 1
	s_branch .Lpv_prio_done
.Lpv_busy:
	s_setprio 3
.Lpv_prio_done:
	ds_read_b64_tr_b16 v[204:205], v200 offset:1536
	ds_read_b64_tr_b16 v[206:207], v200 offset:9728
	s_waitcnt lgkmcnt(6)
	v_mfma_f32_32x32x16_bf16 v[6:21], v[138:141], v[142:145], v[6:21]
	ds_read_b64_tr_b16 v[142:143], v200 offset:2048
	ds_read_b64_tr_b16 v[144:145], v200 offset:10240
	s_waitcnt lgkmcnt(6)
	v_mfma_f32_32x32x16_bf16 v[118:133], v[138:141], v[146:149], v[118:133]
	ds_read_b64_tr_b16 v[146:147], v200 offset:2560
	ds_read_b64_tr_b16 v[148:149], v200 offset:10752
	s_waitcnt lgkmcnt(6)
	v_mfma_f32_32x32x16_bf16 v[102:117], v[138:141], v[248:251], v[102:117]
	ds_read_b64_tr_b16 v[248:249], v200 offset:3072
	ds_read_b64_tr_b16 v[250:251], v200 offset:11264
	s_waitcnt lgkmcnt(6)
	v_mfma_f32_32x32x16_bf16 v[86:101], v[138:141], v[204:207], v[86:101]
	ds_read_b64_tr_b16 v[204:205], v200 offset:3584
	ds_read_b64_tr_b16 v[206:207], v200 offset:11776
	s_waitcnt lgkmcnt(6)
	v_mfma_f32_32x32x16_bf16 v[70:85], v[138:141], v[142:145], v[70:85]
	ds_read_b64_tr_b16 v[142:143], v1 offset:0
	ds_read_b64_tr_b16 v[144:145], v1 offset:8192
	s_waitcnt lgkmcnt(6)
	v_mfma_f32_32x32x16_bf16 v[54:69], v[138:141], v[146:149], v[54:69]
	ds_read_b64_tr_b16 v[146:147], v1 offset:512
	ds_read_b64_tr_b16 v[148:149], v1 offset:8704
	s_waitcnt lgkmcnt(6)
	v_mfma_f32_32x32x16_bf16 v[38:53], v[138:141], v[248:251], v[38:53]
	ds_read_b64_tr_b16 v[248:249], v1 offset:1024
	ds_read_b64_tr_b16 v[250:251], v1 offset:9216
	s_waitcnt lgkmcnt(6)
	v_mfma_f32_32x32x16_bf16 v[22:37], v[138:141], v[204:207], v[22:37]
	ds_read_b64_tr_b16 v[204:205], v1 offset:1536
	ds_read_b64_tr_b16 v[206:207], v1 offset:9728
	s_waitcnt lgkmcnt(6)
	v_mfma_f32_32x32x16_bf16 v[6:21], v[134:137], v[142:145], v[6:21]
	ds_read_b64_tr_b16 v[142:143], v1 offset:2048
	ds_read_b64_tr_b16 v[144:145], v1 offset:10240
	s_waitcnt lgkmcnt(6)
	v_mfma_f32_32x32x16_bf16 v[118:133], v[134:137], v[146:149], v[118:133]
	ds_read_b64_tr_b16 v[146:147], v1 offset:2560
	ds_read_b64_tr_b16 v[148:149], v1 offset:10752
	s_waitcnt lgkmcnt(6)
	v_mfma_f32_32x32x16_bf16 v[102:117], v[134:137], v[248:251], v[102:117]
	ds_read_b64_tr_b16 v[248:249], v1 offset:3072
	ds_read_b64_tr_b16 v[250:251], v1 offset:11264
	s_waitcnt lgkmcnt(6)
	v_mfma_f32_32x32x16_bf16 v[86:101], v[134:137], v[204:207], v[86:101]
	ds_read_b64_tr_b16 v[204:205], v1 offset:3584
	ds_read_b64_tr_b16 v[206:207], v1 offset:11776
	s_waitcnt lgkmcnt(6)
	v_mfma_f32_32x32x16_bf16 v[70:85], v[134:137], v[142:145], v[70:85]
	s_waitcnt lgkmcnt(4)
	v_mfma_f32_32x32x16_bf16 v[54:69], v[134:137], v[146:149], v[54:69]
	s_waitcnt lgkmcnt(2)
	v_mfma_f32_32x32x16_bf16 v[38:53], v[134:137], v[248:251], v[38:53]
	s_waitcnt lgkmcnt(0)
	v_mfma_f32_32x32x16_bf16 v[22:37], v[134:137], v[204:207], v[22:37]
	s_setprio 0
	s_andn2_b64 vcc, exec, s[66:67]
	s_cbranch_vccnz .LBB0_1105
	s_mul_hi_u32 s19, s1, 0xaaaaaaab
	s_lshr_b32 s19, s19, 2
	s_mul_i32 s19, s19, 0xffff0d00
	s_add_i32 s19, s19, 0
	s_add_i32 s19, s19, s81
	v_add_u32_e32 v1, s19, v242
	v_add_u32_e32 v200, s14, v1
	v_add3_u32 v134, v200, v231, v232
	v_add3_u32 v138, v200, v230, v232
	ds_read_b128 v[134:137], v134
	ds_read_b128 v[204:207], v138
	v_add3_u32 v208, v200, v228, v232
	ds_read_b128 v[248:251], v208
	s_setprio 1
	s_waitcnt lgkmcnt(2)
	v_mfma_f32_32x32x16_bf16 v[134:149], v[134:137], v[194:197], 0
	s_waitcnt lgkmcnt(1)
	v_mfma_f32_32x32x16_bf16 v[134:149], v[204:207], v[190:193], v[134:149]
	v_add3_u32 v208, v200, v227, v232
	ds_read_b128 v[204:207], v208
	s_waitcnt lgkmcnt(1)
	v_mfma_f32_32x32x16_bf16 v[134:149], v[248:251], v[186:189], v[134:149]
	v_add3_u32 v208, v200, v236, v232
	ds_read_b128 v[248:251], v208
	s_waitcnt lgkmcnt(1)
	v_mfma_f32_32x32x16_bf16 v[134:149], v[204:207], v[182:185], v[134:149]
	v_add3_u32 v208, v200, v235, v232
	ds_read_b128 v[204:207], v208
	s_waitcnt lgkmcnt(1)
	v_mfma_f32_32x32x16_bf16 v[134:149], v[248:251], v[178:181], v[134:149]
	v_add3_u32 v208, v200, v234, v232
	ds_read_b128 v[248:251], v208
	s_waitcnt lgkmcnt(1)
	v_mfma_f32_32x32x16_bf16 v[134:149], v[204:207], v[174:177], v[134:149]
	v_add3_u32 v208, v200, v233, v232
	ds_read_b128 v[204:207], v208
	s_waitcnt lgkmcnt(1)
	v_mfma_f32_32x32x16_bf16 v[134:149], v[248:251], v[170:173], v[134:149]
	v_add3_u32 v208, v1, v231, v226
	ds_read_b128 v[248:251], v208 offset:8192
	s_waitcnt lgkmcnt(1)
	v_mfma_f32_32x32x16_bf16 v[134:149], v[204:207], v[166:169], v[134:149]
	v_add3_u32 v208, v1, v230, v226
	ds_read_b128 v[204:207], v208 offset:8192
	s_waitcnt lgkmcnt(1)
	v_mfma_f32_32x32x16_bf16 v[134:149], v[248:251], v[162:165], v[134:149]
	v_add3_u32 v208, v1, v228, v226
	ds_read_b128 v[248:251], v208 offset:8192
	s_waitcnt lgkmcnt(1)
	v_mfma_f32_32x32x16_bf16 v[134:149], v[204:207], v[158:161], v[134:149]
	v_add3_u32 v208, v1, v227, v226
	ds_read_b128 v[204:207], v208 offset:8192
	s_waitcnt lgkmcnt(1)
	v_mfma_f32_32x32x16_bf16 v[134:149], v[248:251], v[154:157], v[134:149]
	s_waitcnt lgkmcnt(0)
	v_mfma_f32_32x32x16_bf16 v[134:149], v[204:207], v[150:153], v[134:149]
	s_setprio 0
	v_add_u32_e32 v1, s15, v198
	v_add_u32_e32 v208, s19, v1
	v_add_u32_e32 v1, 0x1b900, v208
	ds_read_b128 v[204:207], v1
	v_add_u32_e32 v1, 0x1b920, v208
	ds_read_b128 v[248:251], v1
	s_waitcnt lgkmcnt(1)
	s_nop 5
	v_fma_f32 v1, v134, v204, -v213
	v_fma_f32 v134, v135, v205, -v213
	v_exp_f32_e32 v1, v1
	v_fma_f32 v135, v136, v206, -v213
	v_exp_f32_e32 v200, v134
	v_fma_f32 v136, v137, v207, -v213
	v_exp_f32_e32 v204, v135
	v_exp_f32_e32 v205, v136
	s_waitcnt lgkmcnt(0)
	v_fma_f32 v135, v138, v248, -v213
	v_add_f32_e32 v134, 0, v1
	v_exp_f32_e32 v206, v135
	v_add_f32_e32 v134, v200, v134
	v_add_f32_e32 v134, v204, v134
	v_add_f32_e32 v134, v205, v134
	v_add_f32_e32 v138, v206, v134
	v_fma_f32 v134, v139, v249, -v213
	v_exp_f32_e32 v207, v134
	v_fma_f32 v134, v140, v250, -v213
	v_exp_f32_e32 v248, v134
	v_fma_f32 v134, v141, v251, -v213
	v_exp_f32_e32 v249, v134
	v_add_u32_e32 v139, 0x1e180, v208
	v_add_f32_e32 v138, v207, v138
	ds_read_b128 v[134:137], v139
	v_add_f32_e32 v138, v248, v138
	v_add_f32_e32 v208, v249, v138
	ds_read_b128 v[138:141], v139 offset:32
	s_waitcnt lgkmcnt(1)
	v_fma_f32 v134, v142, v134, -v213
	v_exp_f32_e32 v134, v134
	v_fma_f32 v135, v143, v135, -v213
	s_waitcnt lgkmcnt(0)
	v_fma_f32 v138, v146, v138, -v213
	v_exp_f32_e32 v135, v135
	v_fma_f32 v136, v144, v136, -v213
	v_exp_f32_e32 v143, v138
	v_fma_f32 v138, v147, v139, -v213
	v_exp_f32_e32 v136, v136
	v_fma_f32 v137, v145, v137, -v213
	v_exp_f32_e32 v144, v138
	v_fma_f32 v138, v148, v140, -v213
	v_exp_f32_e32 v137, v137
	v_exp_f32_e32 v145, v138
	v_fma_f32 v138, v149, v141, -v213
	v_add_f32_e32 v142, v134, v208
	v_exp_f32_e32 v146, v138
	v_add_f32_e32 v142, v135, v142
	v_add_f32_e32 v142, v136, v142
	v_add_f32_e32 v142, v137, v142
	v_cvt_pk_bf16_f32 v138, v1, v200
	v_cvt_pk_bf16_f32 v139, v204, v205
	v_cvt_pk_bf16_f32 v140, v206, v207
	v_cvt_pk_bf16_f32 v141, v248, v249
	s_nop 0
	v_permlane32_swap_b32_e32 v138, v140
	v_permlane32_swap_b32_e32 v139, v141
	v_cvt_pk_bf16_f32 v134, v134, v135
	v_cvt_pk_bf16_f32 v135, v136, v137
	v_cvt_pk_bf16_f32 v136, v143, v144
	v_cvt_pk_bf16_f32 v137, v145, v146
	v_add_f32_e32 v1, v143, v142
	v_permlane32_swap_b32_e32 v134, v136
	v_permlane32_swap_b32_e32 v135, v137
	v_add_f32_e32 v1, v144, v1
	ds_write_b128 v223, v[138:141]
	ds_write_b128 v223, v[134:137] offset:16
	v_add_f32_e32 v1, v145, v1
	s_waitcnt lgkmcnt(0)
	v_add_f32_e32 v1, v146, v1
	v_add_f32_e32 v2, v2, v1
	s_branch .LBB0_1105
	s_nop 0
	s_nop 0
	s_nop 0
	s_nop 0
	s_nop 0
	s_nop 0
	s_nop 0
	s_nop 0
	s_nop 0
	s_nop 0
	s_nop 0
	s_nop 0
